# MLP-up epilogue: canonicalize + relu max pairs fused into one v_max (107 fewer VALU per wave per unit); on top of eb6
# baseline (speedup 1.0000x reference)
.LBB0_1545:
	v_lshl_add_u32 v136, s46, 8, v0
	v_ashrrev_i32_e32 v137, 31, v136
	v_max_f32_e32 v126, 0, v126
	v_lshl_or_b32 v134, s67, 8, v17
	v_lshlrev_b64 v[138:139], 14, v[136:137]
	v_mul_f32_e32 v137, v126, v126
	v_max_f32_e32 v127, 0, v127
	v_max_f32_e32 v128, 0, v128
	v_ashrrev_i32_e32 v135, 31, v134
	v_max_f32_e32 v126, 0, v131
	v_mul_f32_e32 v131, v127, v127
	v_max_f32_e32 v127, v132, v132
	v_mul_f32_e32 v132, v128, v128
	v_lshl_add_u64 v[138:139], s[6:7], 0, v[138:139]
	v_lshlrev_b64 v[140:141], 1, v[134:135]
	v_max_f32_e32 v130, 0, v130
	v_mul_f32_e32 v126, v126, v126
	v_max_f32_e32 v127, 0, v127
	v_max_f32_e32 v128, 0, v133
	v_max_f32_e32 v129, 0, v129
	v_lshl_add_u64 v[134:135], v[138:139], 0, v[140:141]
	v_mul_f32_e32 v130, v130, v130
	v_mul_f32_e32 v127, v127, v127
	v_mul_f32_e32 v128, v128, v128
	v_mul_f32_e32 v129, v129, v129
	v_cvt_pk_bf16_f32 v126, v130, v126
	v_max_f32_e32 v118, 0, v118
	v_cvt_pk_bf16_f32 v127, v127, v128
	v_cvt_pk_bf16_f32 v128, v137, v131
	v_cvt_pk_bf16_f32 v129, v132, v129
	global_store_dwordx4 v[134:135], v[126:129], off
	v_max_f32_e32 v119, 0, v119
	v_max_f32_e32 v120, 0, v120
	v_mul_f32_e32 v126, v118, v118
	v_max_f32_e32 v118, 0, v123
	v_mul_f32_e32 v123, v119, v119
	v_max_f32_e32 v119, v124, v124
	v_mul_f32_e32 v124, v120, v120
	v_max_f32_e32 v122, 0, v122
	v_mul_f32_e32 v118, v118, v118
	v_max_f32_e32 v119, 0, v119
	v_max_f32_e32 v120, 0, v125
	v_max_f32_e32 v121, 0, v121
	v_mul_f32_e32 v122, v122, v122
	v_mul_f32_e32 v119, v119, v119
	v_mul_f32_e32 v120, v120, v120
	v_mul_f32_e32 v121, v121, v121
	v_cvt_pk_bf16_f32 v118, v122, v118
	v_cvt_pk_bf16_f32 v119, v119, v120
	v_cvt_pk_bf16_f32 v120, v126, v123
	v_cvt_pk_bf16_f32 v121, v124, v121
	global_store_dwordx4 v[134:135], v[118:121], off offset:256
	s_nop 1
	v_max_f32_e32 v110, 0, v110
	v_or_b32_e32 v118, 16, v136
	v_ashrrev_i32_e32 v119, 31, v118
	v_mul_f32_e32 v120, v110, v110
	v_max_f32_e32 v111, 0, v111
	v_max_f32_e32 v112, 0, v112
	v_lshlrev_b64 v[118:119], 14, v[118:119]
	v_max_f32_e32 v110, 0, v115
	v_mul_f32_e32 v115, v111, v111
	v_max_f32_e32 v111, v116, v116
	v_mul_f32_e32 v116, v112, v112
	v_lshl_add_u64 v[118:119], s[6:7], 0, v[118:119]
	v_max_f32_e32 v114, 0, v114
	v_mul_f32_e32 v110, v110, v110
	v_max_f32_e32 v111, 0, v111
	v_max_f32_e32 v112, 0, v117
	v_max_f32_e32 v113, 0, v113
	v_lshl_add_u64 v[118:119], v[118:119], 0, v[140:141]
	v_mul_f32_e32 v114, v114, v114
	v_mul_f32_e32 v111, v111, v111
	v_mul_f32_e32 v112, v112, v112
	v_mul_f32_e32 v113, v113, v113
	v_cvt_pk_bf16_f32 v110, v114, v110
	v_max_f32_e32 v102, 0, v102
	v_cvt_pk_bf16_f32 v111, v111, v112
	v_cvt_pk_bf16_f32 v112, v120, v115
	v_cvt_pk_bf16_f32 v113, v116, v113
	global_store_dwordx4 v[118:119], v[110:113], off
	v_max_f32_e32 v103, 0, v103
	v_max_f32_e32 v104, 0, v104
	v_mul_f32_e32 v110, v102, v102
	v_max_f32_e32 v102, 0, v107
	v_mul_f32_e32 v107, v103, v103
	v_max_f32_e32 v103, v108, v108
	v_mul_f32_e32 v108, v104, v104
	v_max_f32_e32 v106, 0, v106
	v_mul_f32_e32 v102, v102, v102
	v_max_f32_e32 v103, 0, v103
	v_max_f32_e32 v104, 0, v109
	v_max_f32_e32 v105, 0, v105
	v_mul_f32_e32 v106, v106, v106
	v_mul_f32_e32 v103, v103, v103
	v_mul_f32_e32 v104, v104, v104
	v_mul_f32_e32 v105, v105, v105
	v_cvt_pk_bf16_f32 v102, v106, v102
	v_cvt_pk_bf16_f32 v103, v103, v104
	v_cvt_pk_bf16_f32 v104, v110, v107
	v_cvt_pk_bf16_f32 v105, v108, v105
	global_store_dwordx4 v[118:119], v[102:105], off offset:256
	s_nop 1
	v_max_f32_e32 v94, 0, v94
	v_or_b32_e32 v102, 32, v136
	v_ashrrev_i32_e32 v103, 31, v102
	v_mul_f32_e32 v104, v94, v94
	v_max_f32_e32 v95, 0, v95
	v_max_f32_e32 v96, 0, v96
	v_lshlrev_b64 v[102:103], 14, v[102:103]
	v_max_f32_e32 v94, 0, v99
	v_mul_f32_e32 v99, v95, v95
	v_max_f32_e32 v95, v100, v100
	v_mul_f32_e32 v100, v96, v96
	v_lshl_add_u64 v[102:103], s[6:7], 0, v[102:103]
	v_max_f32_e32 v98, 0, v98
	v_mul_f32_e32 v94, v94, v94
	v_max_f32_e32 v95, 0, v95
	v_max_f32_e32 v96, 0, v101
	v_max_f32_e32 v97, 0, v97
	v_lshl_add_u64 v[102:103], v[102:103], 0, v[140:141]
	v_mul_f32_e32 v98, v98, v98
	v_mul_f32_e32 v95, v95, v95
	v_mul_f32_e32 v96, v96, v96
	v_mul_f32_e32 v97, v97, v97
	v_cvt_pk_bf16_f32 v94, v98, v94
	v_max_f32_e32 v86, 0, v86
	v_cvt_pk_bf16_f32 v95, v95, v96
	v_cvt_pk_bf16_f32 v96, v104, v99
	v_cvt_pk_bf16_f32 v97, v100, v97
	global_store_dwordx4 v[102:103], v[94:97], off
	v_max_f32_e32 v87, 0, v87
	v_max_f32_e32 v88, 0, v88
	v_mul_f32_e32 v94, v86, v86
	v_max_f32_e32 v86, 0, v91
	v_mul_f32_e32 v91, v87, v87
	v_max_f32_e32 v87, v92, v92
	v_mul_f32_e32 v92, v88, v88
	v_max_f32_e32 v90, 0, v90
	v_mul_f32_e32 v86, v86, v86
	v_max_f32_e32 v87, 0, v87
	v_max_f32_e32 v88, 0, v93
	v_max_f32_e32 v89, 0, v89
	v_mul_f32_e32 v90, v90, v90
	v_mul_f32_e32 v87, v87, v87
	v_mul_f32_e32 v88, v88, v88
	v_mul_f32_e32 v89, v89, v89
	v_cvt_pk_bf16_f32 v86, v90, v86
	v_cvt_pk_bf16_f32 v87, v87, v88
	v_cvt_pk_bf16_f32 v88, v94, v91
	v_cvt_pk_bf16_f32 v89, v92, v89
	global_store_dwordx4 v[102:103], v[86:89], off offset:256
	s_nop 1
	v_max_f32_e32 v78, 0, v78
	v_or_b32_e32 v86, 48, v136
	v_ashrrev_i32_e32 v87, 31, v86
	v_mul_f32_e32 v88, v78, v78
	v_max_f32_e32 v79, 0, v79
	v_max_f32_e32 v80, 0, v80
	v_lshlrev_b64 v[86:87], 14, v[86:87]
	v_max_f32_e32 v78, 0, v83
	v_mul_f32_e32 v83, v79, v79
	v_max_f32_e32 v79, v84, v84
	v_mul_f32_e32 v84, v80, v80
	v_lshl_add_u64 v[86:87], s[6:7], 0, v[86:87]
	v_max_f32_e32 v82, 0, v82
	v_mul_f32_e32 v78, v78, v78
	v_max_f32_e32 v79, 0, v79
	v_max_f32_e32 v80, 0, v85
	v_max_f32_e32 v81, 0, v81
	v_lshl_add_u64 v[86:87], v[86:87], 0, v[140:141]
	v_mul_f32_e32 v82, v82, v82
	v_mul_f32_e32 v79, v79, v79
	v_mul_f32_e32 v80, v80, v80
	v_mul_f32_e32 v81, v81, v81
	v_cvt_pk_bf16_f32 v78, v82, v78
	v_max_f32_e32 v70, 0, v70
	v_max_f32_e32 v71, 0, v71
	v_max_f32_e32 v72, 0, v72
	v_cvt_pk_bf16_f32 v79, v79, v80
	v_cvt_pk_bf16_f32 v80, v88, v83
	v_cvt_pk_bf16_f32 v81, v84, v81
	global_store_dwordx4 v[86:87], v[78:81], off
	s_nop 1
	v_mul_f32_e32 v78, v70, v70
	v_max_f32_e32 v70, v75, v75
	v_mul_f32_e32 v75, v71, v71
	v_max_f32_e32 v71, v76, v76
	v_mul_f32_e32 v76, v72, v72
	v_max_f32_e32 v70, 0, v70
	v_max_f32_e32 v71, 0, v71
	v_max_f32_e32 v72, 0, v77
	v_max_f32_e32 v74, 0, v74
	v_mul_f32_e32 v70, v70, v70
	v_mul_f32_e32 v71, v71, v71
	v_max_f32_e32 v73, 0, v73
	v_mul_f32_e32 v72, v72, v72
	v_mul_f32_e32 v74, v74, v74
	v_mul_f32_e32 v73, v73, v73
	v_cvt_pk_bf16_f32 v70, v74, v70
	v_cvt_pk_bf16_f32 v71, v71, v72
	v_cvt_pk_bf16_f32 v72, v78, v75
	v_max_f32_e32 v62, 0, v62
	v_cvt_pk_bf16_f32 v73, v76, v73
	global_store_dwordx4 v[86:87], v[70:73], off offset:256
	s_nop 1
	v_max_f32_e32 v63, 0, v63
	v_mul_f32_e32 v72, v62, v62
	v_max_f32_e32 v64, 0, v64
	v_max_f32_e32 v66, 0, v66
	v_max_f32_e32 v62, 0, v67
	v_mul_f32_e32 v67, v63, v63
	v_max_f32_e32 v63, v68, v68
	v_mul_f32_e32 v68, v64, v64
	v_mul_f32_e32 v66, v66, v66
	v_mul_f32_e32 v62, v62, v62
	v_max_f32_e32 v63, 0, v63
	v_max_f32_e32 v64, 0, v69
	s_mov_b32 s11, 0x200000
	v_mul_f32_e32 v63, v63, v63
	v_max_f32_e32 v65, 0, v65
	v_mul_f32_e32 v64, v64, v64
	v_cvt_pk_bf16_f32 v62, v66, v62
	v_add_co_u32_e32 v66, vcc, s11, v134
	v_mul_f32_e32 v65, v65, v65
	v_cvt_pk_bf16_f32 v63, v63, v64
	v_cvt_pk_bf16_f32 v64, v72, v67
	v_addc_co_u32_e32 v67, vcc, 0, v135, vcc
	v_max_f32_e32 v54, 0, v54
	v_max_f32_e32 v55, 0, v55
	v_max_f32_e32 v56, 0, v56
	v_cvt_pk_bf16_f32 v65, v68, v65
	global_store_dwordx4 v[66:67], v[62:65], off
	s_nop 1
	v_mul_f32_e32 v62, v54, v54
	v_max_f32_e32 v54, v59, v59
	v_mul_f32_e32 v59, v55, v55
	v_max_f32_e32 v55, v60, v60
	v_mul_f32_e32 v60, v56, v56
	v_max_f32_e32 v54, 0, v54
	v_max_f32_e32 v55, 0, v55
	v_max_f32_e32 v56, 0, v61
	s_mov_b64 s[48:49], 0x200000
	v_max_f32_e32 v58, 0, v58
	v_mul_f32_e32 v54, v54, v54
	v_mul_f32_e32 v55, v55, v55
	v_max_f32_e32 v57, 0, v57
	v_mul_f32_e32 v56, v56, v56
	v_lshl_add_u64 v[70:71], v[134:135], 0, s[48:49]
	v_mul_f32_e32 v58, v58, v58
	v_mul_f32_e32 v57, v57, v57
	v_cvt_pk_bf16_f32 v54, v58, v54
	v_cvt_pk_bf16_f32 v55, v55, v56
	v_cvt_pk_bf16_f32 v56, v62, v59
	v_max_f32_e32 v46, 0, v46
	v_cvt_pk_bf16_f32 v57, v60, v57
	global_store_dwordx4 v[70:71], v[54:57], off offset:256
	s_nop 1
	v_max_f32_e32 v47, 0, v47
	v_mul_f32_e32 v56, v46, v46
	v_max_f32_e32 v48, 0, v48
	v_max_f32_e32 v50, 0, v50
	v_max_f32_e32 v46, 0, v51
	v_mul_f32_e32 v51, v47, v47
	v_max_f32_e32 v47, v52, v52
	v_mul_f32_e32 v52, v48, v48
	v_mul_f32_e32 v50, v50, v50
	v_mul_f32_e32 v46, v46, v46
	v_max_f32_e32 v47, 0, v47
	v_max_f32_e32 v48, 0, v53
	s_mov_b32 s11, 0x240000
	v_mul_f32_e32 v47, v47, v47
	v_max_f32_e32 v49, 0, v49
	v_mul_f32_e32 v48, v48, v48
	v_cvt_pk_bf16_f32 v46, v50, v46
	v_add_co_u32_e32 v50, vcc, s11, v134
	v_mul_f32_e32 v49, v49, v49
	v_cvt_pk_bf16_f32 v47, v47, v48
	v_cvt_pk_bf16_f32 v48, v56, v51
	v_addc_co_u32_e32 v51, vcc, 0, v135, vcc
	v_max_f32_e32 v38, 0, v38
	v_max_f32_e32 v39, 0, v39
	v_max_f32_e32 v40, 0, v40
	v_cvt_pk_bf16_f32 v49, v52, v49
	global_store_dwordx4 v[50:51], v[46:49], off
	s_nop 1
	v_mul_f32_e32 v46, v38, v38
	v_max_f32_e32 v38, v43, v43
	v_mul_f32_e32 v43, v39, v39
	v_max_f32_e32 v39, v44, v44
	v_mul_f32_e32 v44, v40, v40
	v_max_f32_e32 v38, 0, v38
	v_max_f32_e32 v39, 0, v39
	v_max_f32_e32 v40, 0, v45
	s_mov_b64 s[48:49], 0x240000
	v_max_f32_e32 v42, 0, v42
	v_mul_f32_e32 v38, v38, v38
	v_mul_f32_e32 v39, v39, v39
	v_max_f32_e32 v41, 0, v41
	v_mul_f32_e32 v40, v40, v40
	v_lshl_add_u64 v[54:55], v[134:135], 0, s[48:49]
	v_mul_f32_e32 v42, v42, v42
	v_mul_f32_e32 v41, v41, v41
	v_cvt_pk_bf16_f32 v38, v42, v38
	v_cvt_pk_bf16_f32 v39, v39, v40
	v_cvt_pk_bf16_f32 v40, v46, v43
	v_max_f32_e32 v30, 0, v30
	v_cvt_pk_bf16_f32 v41, v44, v41
	global_store_dwordx4 v[54:55], v[38:41], off offset:256
	s_nop 1
	v_max_f32_e32 v31, 0, v31
	v_mul_f32_e32 v40, v30, v30
	v_max_f32_e32 v32, 0, v32
	v_max_f32_e32 v34, 0, v34
	v_max_f32_e32 v30, 0, v35
	v_mul_f32_e32 v35, v31, v31
	v_max_f32_e32 v31, v36, v36
	v_mul_f32_e32 v36, v32, v32
	v_mul_f32_e32 v34, v34, v34
	v_mul_f32_e32 v30, v30, v30
	v_max_f32_e32 v31, 0, v31
	v_max_f32_e32 v32, 0, v37
	s_mov_b32 s11, 0x280000
	v_mul_f32_e32 v31, v31, v31
	v_max_f32_e32 v33, 0, v33
	v_mul_f32_e32 v32, v32, v32
	v_cvt_pk_bf16_f32 v30, v34, v30
	v_add_co_u32_e32 v34, vcc, s11, v134
	v_mul_f32_e32 v33, v33, v33
	v_cvt_pk_bf16_f32 v31, v31, v32
	v_cvt_pk_bf16_f32 v32, v40, v35
	v_addc_co_u32_e32 v35, vcc, 0, v135, vcc
	v_max_f32_e32 v22, 0, v22
	v_max_f32_e32 v23, 0, v23
	v_max_f32_e32 v24, 0, v24
	v_cvt_pk_bf16_f32 v33, v36, v33
	global_store_dwordx4 v[34:35], v[30:33], off
	s_nop 1
	v_mul_f32_e32 v30, v22, v22
	v_max_f32_e32 v22, v27, v27
	v_mul_f32_e32 v27, v23, v23
	v_max_f32_e32 v23, v28, v28
	v_mul_f32_e32 v28, v24, v24
	v_max_f32_e32 v22, 0, v22
	v_max_f32_e32 v23, 0, v23
	v_max_f32_e32 v24, 0, v29
	s_mov_b64 s[48:49], 0x280000
	v_max_f32_e32 v26, 0, v26
	v_mul_f32_e32 v22, v22, v22
	v_mul_f32_e32 v23, v23, v23
	v_max_f32_e32 v25, 0, v25
	v_mul_f32_e32 v24, v24, v24
	v_lshl_add_u64 v[38:39], v[134:135], 0, s[48:49]
	v_mul_f32_e32 v26, v26, v26
	v_mul_f32_e32 v25, v25, v25
	v_cvt_pk_bf16_f32 v22, v26, v22
	v_cvt_pk_bf16_f32 v23, v23, v24
	v_cvt_pk_bf16_f32 v24, v30, v27
	v_max_f32_e32 v10, 0, v10
	v_cvt_pk_bf16_f32 v25, v28, v25
	global_store_dwordx4 v[38:39], v[22:25], off offset:256
	s_nop 1
	v_max_f32_e32 v11, 0, v11
	v_mul_f32_e32 v24, v10, v10
	v_max_f32_e32 v12, 0, v12
	v_max_f32_e32 v18, 0, v18
	v_max_f32_e32 v10, 0, v19
	v_mul_f32_e32 v19, v11, v11
	v_max_f32_e32 v11, v20, v20
	v_mul_f32_e32 v20, v12, v12
	v_mul_f32_e32 v18, v18, v18
	v_mul_f32_e32 v10, v10, v10
	v_max_f32_e32 v11, 0, v11
	v_max_f32_e32 v12, 0, v21
	s_mov_b32 s11, 0x2c0000
	v_mul_f32_e32 v11, v11, v11
	v_max_f32_e32 v13, 0, v13
	v_mul_f32_e32 v12, v12, v12
	v_cvt_pk_bf16_f32 v10, v18, v10
	v_add_co_u32_e32 v18, vcc, s11, v134
	v_mul_f32_e32 v13, v13, v13
	v_cvt_pk_bf16_f32 v11, v11, v12
	v_cvt_pk_bf16_f32 v12, v24, v19
	v_addc_co_u32_e32 v19, vcc, 0, v135, vcc
	v_max_f32_e32 v2, 0, v2
	v_max_f32_e32 v3, 0, v3
	v_max_f32_e32 v4, 0, v4
	v_cvt_pk_bf16_f32 v13, v20, v13
	global_store_dwordx4 v[18:19], v[10:13], off
	s_nop 1
	s_mov_b64 s[48:49], 0x2c0000
	v_mul_f32_e32 v10, v2, v2
	v_max_f32_e32 v2, v7, v7
	v_mul_f32_e32 v7, v3, v3
	v_max_f32_e32 v3, v8, v8
	v_mul_f32_e32 v8, v4, v4
	v_max_f32_e32 v2, 0, v2
	v_max_f32_e32 v3, 0, v3
	v_max_f32_e32 v4, 0, v9
	v_max_f32_e32 v5, 0, v5
	v_lshl_add_u64 v[22:23], v[134:135], 0, s[48:49]
	v_max_f32_e32 v6, 0, v6
	v_mul_f32_e32 v2, v2, v2
	v_mul_f32_e32 v3, v3, v3
	v_mul_f32_e32 v4, v4, v4
	v_mul_f32_e32 v5, v5, v5
	s_andn2_b64 vcc, exec, s[40:41]
	s_mov_b64 s[40:41], -1
	v_mul_f32_e32 v6, v6, v6
	v_cvt_pk_bf16_f32 v2, v6, v2
	v_cvt_pk_bf16_f32 v3, v3, v4
	v_cvt_pk_bf16_f32 v4, v10, v7
	v_cvt_pk_bf16_f32 v5, v8, v5
	global_store_dwordx4 v[22:23], v[2:5], off offset:256
	s_cbranch_vccnz .LBB0_1523
	s_andn2_b64 vcc, exec, s[4:5]
	s_cbranch_vccnz .LBB0_1522
	s_barrier
	s_branch .LBB0_1522
